# stack5 + scan1 triangular-solve row reads narrowed (no overlapping destinations, one lgkmcnt wait instead of eight drains) + scan2 SC stores issued under the LDS reads/MFMA chain
# speedup vs baseline: 1.0067x; 1.0067x over previous
; #define LAS __attribute__((address_space(3)))
; __device__ __forceinline__ f32x4 mma16(bf16x8 a, bf16x8 b, f32x4 c) { return __builtin_amdgcn_mfma_f32_16x16x32_bf16(a, b, c, 0, 0, 0); }
; __device__ __forceinline__ void phase_scan1(Frame& F, int l) {
;     ...
;         {   STAGE_LANE; bf16x8 a_[2];
; #pragma unroll
;             for (int ks = 0; ks < 2; ++ks) a_[ks] = frag(AKK, tm, ks, lane);
; #pragma unroll
;             for (int q = 0; q < 2; ++q) { const int tn = tn0 + q; f32x4 acc = {0.f, 0.f, 0.f, 0.f};
; #pragma unroll
;                 for (int ks = 0; ks < 2; ++ks) acc = mma16(frag(VT, tn, ks, lane), a_[ks], acc);
;                 *(LAS f32x4*)(XF + (16 * tm + fr) * XP + 16 * tn + 4 * fq) = acc; }
;             if (w == 0) { const int bb = lane >> 4, cc = lane & 15; float x[16];
;                 f32x4 Lr[16][4];
; #pragma unroll
;                 for (int t = 1; t < 16; ++t)
; #pragma unroll
;                     for (int q4 = 0; q4 < (t + 3) / 4; ++q4) Lr[t][q4] = *(const LAS f32x4*)(LD + (bb * 16 + t) * 16 + 4 * q4);
.LBB0_548:
	v_mov_b32_e32 v0, v85
	s_waitcnt lgkmcnt(0)
	s_barrier
	s_and_b64 vcc, exec, s[6:7]
	s_waitcnt lgkmcnt(2)
	s_nop 0
	v_and_b32_e32 v42, 15, v0
	v_and_b32_e32 v43, -16, v0
	v_add_u32_e32 v61, v88, v43
	v_or_b32_e32 v44, s66, v42
	s_waitcnt lgkmcnt(0)
	v_mad_u32_u24 v48, v44, s86, v61
	ds_read_b128 v[44:47], v48
	v_or_b32_e32 v60, s58, v42
	v_mul_lo_u32 v49, v60, s86
	v_add3_u32 v56, v93, v49, v43
	ds_read_b128 v[48:51], v48 offset:64
	ds_read_b128 v[52:55], v56
	ds_read_b128 v[56:59], v56 offset:64
	s_waitcnt lgkmcnt(1)
	v_mfma_f32_16x16x32_bf16 v[44:47], v[44:47], v[52:55], 0
	v_mul_lo_u32 v60, v60, s76
	v_add3_u32 v60, v96, v60, v43
	s_waitcnt lgkmcnt(0)
	v_mfma_f32_16x16x32_bf16 v[44:47], v[48:51], v[56:59], v[44:47]
	v_add_u32_e32 v48, s82, v60
	s_nop 6
	ds_write_b128 v48, v[44:47]
	v_or_b32_e32 v44, s46, v42
	v_mad_u32_u24 v48, v44, s86, v61
	ds_read_b128 v[44:47], v48
	ds_read_b128 v[48:51], v48 offset:64
	s_waitcnt lgkmcnt(1)
	v_mfma_f32_16x16x32_bf16 v[44:47], v[44:47], v[52:55], 0
	s_waitcnt lgkmcnt(0)
	v_mfma_f32_16x16x32_bf16 v[44:47], v[48:51], v[56:59], v[44:47]
	v_add_u32_e32 v48, s83, v60
	s_nop 6
	ds_write_b128 v48, v[44:47]
	s_cbranch_vccnz .LBB0_550
	v_lshl_add_u32 v72, v43, 6, v97
	ds_read_b32 v44, v72 offset:64
	ds_read_b64 v[46:47], v72 offset:128
	ds_read_b128 v[48:51], v72 offset:192
	ds_read_b128 v[52:55], v72 offset:256
	ds_read_b128 v[56:59], v72 offset:320
	ds_read_b64 v[60:61], v72 offset:336
	ds_read_b128 v[62:65], v72 offset:384
	ds_read_b64 v[66:67], v72 offset:400
	ds_read_b128 v[68:71], v72 offset:448
	ds_read_b128 v[126:129], v72 offset:464
	ds_read_b128 v[130:133], v72 offset:512
	ds_read_b128 v[134:137], v72 offset:528
	ds_read_b128 v[138:141], v72 offset:576
	ds_read_b128 v[142:145], v72 offset:592
	ds_read_b64 v[146:147], v72 offset:608
	ds_read_b128 v[148:151], v72 offset:640
	ds_read_b128 v[152:155], v72 offset:656
	ds_read_b64 v[156:157], v72 offset:672
	ds_read_b128 v[158:161], v72 offset:704
	ds_read_b128 v[162:165], v72 offset:720
	ds_read_b128 v[166:169], v72 offset:736
	ds_read_b128 v[170:173], v72 offset:768
	ds_read_b128 v[174:177], v72 offset:784
	ds_read_b128 v[178:181], v72 offset:800
	ds_read_b128 v[182:185], v72 offset:832
	ds_read_b128 v[186:189], v72 offset:848
	ds_read_b128 v[190:193], v72 offset:864
	ds_read_b64 v[208:209], v72 offset:880
	v_lshl_or_b32 v45, v0, 6, v236
	ds_read_b128 v[210:213], v72 offset:896
	ds_read_b128 v[214:217], v72 offset:912
	ds_read_b128 v[218:221], v72 offset:928
	ds_read_b64 v[222:223], v72 offset:944
	v_add_u32_e32 v45, v97, v45
	v_cmp_eq_u32_e32 vcc, 0, v42
	ds_read_b128 v[224:227], v45
	ds_read_b128 v[228:231], v45 offset:16
	ds_read_b128 v[232:235], v45 offset:32
	ds_read_b128 v[248:251], v45 offset:48
	s_waitcnt lgkmcnt(4)
; #define LAS __attribute__((address_space(3)))
; __device__ __forceinline__ unsigned f2bf(float f) { return pk2(f, f) & 0xffffu; }
; __device__ __forceinline__ void phase_scan1(Frame& F, int l) {
;     ...
;             if (w == 0) { const int bb = lane >> 4, cc = lane & 15; float x[16];
;                 f32x4 Lr[16][4];
; #pragma unroll
;                 for (int t = 1; t < 16; ++t)
; #pragma unroll
;                     for (int q4 = 0; q4 < (t + 3) / 4; ++q4) Lr[t][q4] = *(const LAS f32x4*)(LD + (bb * 16 + t) * 16 + 4 * q4);
; #pragma unroll
;                 for (int t = 0; t < 16; ++t) { float acc = (t == cc) ? 1.f : 0.f;
; #pragma unroll
;                     for (int sI = 0; sI < t; ++sI) acc -= Lr[t][sI >> 2][sI & 3] * x[sI];
;                     x[t] = acc; }
; #pragma unroll
;                 for (int t = 0; t < 16; ++t) TBt[(bb * 16 + t) * TBP + cc] = (bf16)f2bf(x[t]); }
	v_cndmask_b32_e64 v45, 0, 1.0, vcc
	v_cmp_eq_u32_e32 vcc, 1, v42
	v_cvt_pk_bf16_f32 v61, v45, s0
	v_or_b32_e32 v0, 15, v0
	v_cndmask_b32_e64 v51, 0, 1.0, vcc
	v_cmp_eq_u32_e32 vcc, 2, v42
	v_fma_f32 v51, -v45, v44, v51
	s_nop 0
	v_cndmask_b32_e64 v44, 0, 1.0, vcc
	v_fma_f32 v44, -v45, v46, v44
	v_cmp_eq_u32_e32 vcc, 3, v42
	v_fma_f32 v46, -v47, v51, v44
	s_nop 0
	v_cndmask_b32_e64 v44, 0, 1.0, vcc
	v_fma_f32 v44, -v45, v48, v44
	v_fma_f32 v44, -v49, v51, v44
	v_cmp_eq_u32_e32 vcc, 4, v42
	v_fma_f32 v47, -v50, v46, v44
	s_nop 0
	v_cndmask_b32_e64 v44, 0, 1.0, vcc
	v_fma_f32 v44, -v45, v52, v44
	v_fma_f32 v44, -v51, v53, v44
	v_fma_f32 v44, -v54, v46, v44
	v_cmp_eq_u32_e32 vcc, 5, v42
	v_fma_f32 v48, -v55, v47, v44
	s_nop 0
	v_cndmask_b32_e64 v44, 0, 1.0, vcc
	v_fma_f32 v44, -v45, v56, v44
	v_fma_f32 v44, -v51, v57, v44
	v_fma_f32 v44, -v58, v46, v44
	v_fma_f32 v44, -v59, v47, v44
	v_cmp_eq_u32_e32 vcc, 6, v42
	v_fma_f32 v49, -v60, v48, v44
	s_nop 0
	v_cndmask_b32_e64 v44, 0, 1.0, vcc
	v_fma_f32 v44, -v45, v62, v44
	v_fma_f32 v44, -v51, v63, v44
	v_fma_f32 v44, -v46, v64, v44
	v_fma_f32 v44, -v65, v47, v44
	v_fma_f32 v44, -v66, v48, v44
	v_cmp_eq_u32_e32 vcc, 7, v42
	v_fma_f32 v50, -v67, v49, v44
	s_nop 0
	v_cndmask_b32_e64 v44, 0, 1.0, vcc
	v_fma_f32 v44, -v45, v68, v44
	v_fma_f32 v44, -v51, v69, v44
	v_fma_f32 v44, -v46, v70, v44
	v_fma_f32 v44, -v47, v71, v44
	v_fma_f32 v44, -v48, v126, v44
	v_fma_f32 v44, -v127, v49, v44
	v_cmp_eq_u32_e32 vcc, 8, v42
	v_fma_f32 v52, -v128, v50, v44
	s_nop 0
	v_cndmask_b32_e64 v44, 0, 1.0, vcc
	v_fma_f32 v44, -v45, v130, v44
	v_fma_f32 v44, -v51, v131, v44
	v_fma_f32 v44, -v46, v132, v44
	v_fma_f32 v44, -v47, v133, v44
	v_fma_f32 v44, -v48, v134, v44
	v_fma_f32 v44, -v49, v135, v44
	v_fma_f32 v44, -v136, v50, v44
	v_cmp_eq_u32_e32 vcc, 9, v42
	v_fma_f32 v53, -v137, v52, v44
	s_nop 0
	v_cndmask_b32_e64 v44, 0, 1.0, vcc
	v_fma_f32 v44, -v45, v138, v44
	v_fma_f32 v44, -v51, v139, v44
	v_fma_f32 v44, -v46, v140, v44
	v_fma_f32 v44, -v47, v141, v44
	v_fma_f32 v44, -v48, v142, v44
	v_fma_f32 v44, -v49, v143, v44
	v_fma_f32 v44, -v144, v50, v44
	v_fma_f32 v44, -v145, v52, v44
	v_cmp_eq_u32_e32 vcc, 10, v42
	v_fma_f32 v54, -v146, v53, v44
	s_nop 0
	v_cndmask_b32_e64 v44, 0, 1.0, vcc
	v_fma_f32 v44, -v45, v148, v44
	v_fma_f32 v44, -v51, v149, v44
	v_fma_f32 v44, -v46, v150, v44
	v_fma_f32 v44, -v47, v151, v44
	v_fma_f32 v44, -v48, v152, v44
	v_fma_f32 v44, -v49, v153, v44
	v_fma_f32 v44, -v50, v154, v44
	v_fma_f32 v44, -v155, v52, v44
	v_fma_f32 v44, -v156, v53, v44
	v_cmp_eq_u32_e32 vcc, 11, v42
	v_fma_f32 v55, -v157, v54, v44
	s_nop 0
	v_cndmask_b32_e64 v44, 0, 1.0, vcc
	v_fma_f32 v44, -v45, v158, v44
	v_fma_f32 v44, -v51, v159, v44
	v_fma_f32 v44, -v46, v160, v44
	v_fma_f32 v44, -v47, v161, v44
	v_fma_f32 v44, -v48, v162, v44
	v_fma_f32 v44, -v49, v163, v44
	v_fma_f32 v44, -v50, v164, v44
	v_fma_f32 v44, -v52, v165, v44
	v_fma_f32 v44, -v53, v166, v44
	v_fma_f32 v44, -v167, v54, v44
	v_cmp_eq_u32_e32 vcc, 12, v42
	v_fma_f32 v56, -v168, v55, v44
	s_nop 0
	v_cndmask_b32_e64 v44, 0, 1.0, vcc
	v_fma_f32 v44, -v45, v170, v44
	v_fma_f32 v44, -v51, v171, v44
	v_fma_f32 v44, -v46, v172, v44
	v_fma_f32 v44, -v47, v173, v44
	v_fma_f32 v44, -v48, v174, v44
	v_fma_f32 v44, -v49, v175, v44
	v_fma_f32 v44, -v50, v176, v44
	v_fma_f32 v44, -v52, v177, v44
	v_fma_f32 v44, -v53, v178, v44
	v_fma_f32 v44, -v54, v179, v44
	v_fma_f32 v44, -v180, v55, v44
	v_cmp_eq_u32_e32 vcc, 13, v42
	v_fma_f32 v57, -v181, v56, v44
	s_nop 0
	v_cndmask_b32_e64 v44, 0, 1.0, vcc
	v_fma_f32 v44, -v45, v182, v44
	v_fma_f32 v44, -v51, v183, v44
	v_fma_f32 v44, -v46, v184, v44
	v_fma_f32 v44, -v47, v185, v44
	v_fma_f32 v44, -v48, v186, v44
	v_fma_f32 v44, -v49, v187, v44
	v_fma_f32 v44, -v50, v188, v44
	v_fma_f32 v44, -v52, v189, v44
	v_fma_f32 v44, -v53, v190, v44
	v_fma_f32 v44, -v54, v191, v44
	v_fma_f32 v44, -v192, v55, v44
	v_fma_f32 v44, -v193, v56, v44
	v_cmp_eq_u32_e32 vcc, 14, v42
	v_fma_f32 v58, -v208, v57, v44
	s_nop 0
	v_cndmask_b32_e64 v44, 0, 1.0, vcc
	v_fma_f32 v44, -v45, v210, v44
	v_fma_f32 v44, -v51, v211, v44
	v_fma_f32 v44, -v46, v212, v44
	v_fma_f32 v44, -v47, v213, v44
	v_fma_f32 v44, -v48, v214, v44
	v_fma_f32 v44, -v49, v215, v44
	v_fma_f32 v44, -v50, v216, v44
	v_fma_f32 v44, -v52, v217, v44
	v_fma_f32 v44, -v53, v218, v44
	v_fma_f32 v44, -v54, v219, v44
	v_fma_f32 v44, -v55, v220, v44
	v_fma_f32 v44, -v221, v56, v44
	v_fma_f32 v44, -v222, v57, v44
	v_cmp_eq_u32_e32 vcc, 15, v42
	v_fma_f32 v59, -v223, v58, v44
	v_lshl_add_u32 v42, v42, 1, v97
	v_cndmask_b32_e64 v44, 0, 1.0, vcc
	s_waitcnt lgkmcnt(3)
	v_fma_f32 v44, -v45, v224, v44
	v_fma_f32 v44, -v51, v225, v44
	v_fma_f32 v44, -v46, v226, v44
	v_fma_f32 v44, -v47, v227, v44
	s_waitcnt lgkmcnt(2)
	v_fma_f32 v44, -v48, v228, v44
	v_fma_f32 v44, -v49, v229, v44
	v_fma_f32 v44, -v50, v230, v44
	v_fma_f32 v44, -v52, v231, v44
	s_waitcnt lgkmcnt(1)
	v_fma_f32 v44, -v53, v232, v44
	v_fma_f32 v44, -v54, v233, v44
	v_fma_f32 v44, -v55, v234, v44
	v_fma_f32 v44, -v56, v235, v44
	s_waitcnt lgkmcnt(0)
	v_fma_f32 v44, -v57, v248, v44
	v_fma_f32 v44, -v249, v58, v44
	v_fma_f32 v60, -v250, v59, v44
	v_mad_u64_u32 v[44:45], s[6:7], v43, s87, v[42:43]
	v_cvt_pk_bf16_f32 v43, v51, s0
	ds_write_b16 v44, v43 offset:6480
	v_cvt_pk_bf16_f32 v43, v46, s0
	ds_write_b16 v44, v43 offset:6560
	v_cvt_pk_bf16_f32 v43, v47, s0
	ds_write_b16 v44, v43 offset:6640
	v_cvt_pk_bf16_f32 v43, v48, s0
	ds_write_b16 v44, v43 offset:6720
	v_cvt_pk_bf16_f32 v43, v49, s0
	ds_write_b16 v44, v43 offset:6800
	v_cvt_pk_bf16_f32 v43, v50, s0
	ds_write_b16 v44, v43 offset:6880
	v_cvt_pk_bf16_f32 v43, v52, s0
	ds_write_b16 v44, v43 offset:6960
	v_cvt_pk_bf16_f32 v43, v53, s0
	ds_write_b16 v44, v43 offset:7040
	v_cvt_pk_bf16_f32 v43, v54, s0
	ds_write_b16 v44, v43 offset:7120
	v_cvt_pk_bf16_f32 v43, v55, s0
	ds_write_b16 v44, v43 offset:7200
	v_cvt_pk_bf16_f32 v43, v56, s0
	ds_write_b16 v44, v43 offset:7280
	v_cvt_pk_bf16_f32 v43, v57, s0
	ds_write_b16 v44, v43 offset:7360
	v_cvt_pk_bf16_f32 v43, v58, s0
	ds_write_b16 v44, v43 offset:7440
	v_cvt_pk_bf16_f32 v43, v59, s0
	ds_write_b16 v44, v61 offset:6400
	ds_write_b16 v44, v43 offset:7520
	v_cvt_pk_bf16_f32 v44, v60, s0
	v_mad_u64_u32 v[42:43], s[6:7], v0, s87, v[42:43]
	ds_write_b16 v42, v44 offset:6400

.LBB0_663:
	s_add_i32 s11, s27, s36
	s_add_i32 s30, s11, -8
	s_ashr_i32 s31, s30, 31
	s_lshl_b64 s[30:31], s[30:31], 13
	v_lshl_add_u64 v[102:103], v[62:63], 0, s[30:31]
	v_cvt_pk_bf16_f32 v98, v36, s0
	v_cvt_pk_bf16_f32 v99, v37, s0
	v_cvt_pk_bf16_f32 v100, v38, s0
	v_cvt_pk_bf16_f32 v101, v39, s0
	v_add_u32_e32 v0, v66, v72
	ds_read2st64_b32 v[36:37], v0 offset0:72 offset1:73
	ds_read_b32 v38, v0 offset:18944
	v_add_u32_e32 v0, v66, v73
	ds_read_b32 v39, v0 offset:18432
	ds_read_b128 v[74:77], v67
	ds_read_b128 v[78:81], v68 offset:26624
	ds_read_b128 v[82:85], v68 offset:28928
	ds_read_b128 v[86:89], v67 offset:64
	ds_read_b128 v[90:93], v68 offset:26688
	ds_read_b128 v[94:97], v68 offset:28992
	global_store_short v[102:103], v98, off
	global_store_short v[102:103], v99, off offset:128
	s_waitcnt lgkmcnt(4)
	v_mfma_f32_16x16x32_bf16 v[36:39], v[78:81], v[74:77], v[36:39]
	global_store_short v[102:103], v100, off offset:256
	s_waitcnt lgkmcnt(3)
	v_mfma_f32_16x16x32_bf16 v[36:39], v[82:85], v[74:77], v[36:39]
	global_store_short v[102:103], v101, off offset:384
	s_waitcnt lgkmcnt(1)
	v_mfma_f32_16x16x32_bf16 v[36:39], v[90:93], v[86:89], v[36:39]
	s_waitcnt lgkmcnt(0)
	v_mfma_f32_16x16x32_bf16 v[36:39], v[94:97], v[86:89], v[36:39]

.LBB0_670:
	s_add_i32 s11, s27, s36
	s_add_i32 s30, s11, -7
	s_ashr_i32 s31, s30, 31
	s_lshl_b64 s[30:31], s[30:31], 13
	v_lshl_add_u64 v[102:103], v[62:63], 0, s[30:31]
	v_cvt_pk_bf16_f32 v98, v36, s0
	v_cvt_pk_bf16_f32 v99, v37, s0
	v_cvt_pk_bf16_f32 v100, v38, s0
	v_cvt_pk_bf16_f32 v101, v39, s0
	v_add_u32_e32 v0, v69, v72
	ds_read2st64_b32 v[36:37], v0 offset0:88 offset1:89
	ds_read_b32 v38, v0 offset:23040
	v_add_u32_e32 v0, v69, v73
	ds_read_b32 v39, v0 offset:22528
	ds_read_b128 v[74:77], v67 offset:9216
	ds_read_b128 v[78:81], v68 offset:26624
	ds_read_b128 v[82:85], v68 offset:28928
	ds_read_b128 v[86:89], v67 offset:9280
	ds_read_b128 v[90:93], v68 offset:26688
	ds_read_b128 v[94:97], v68 offset:28992
	global_store_short v[102:103], v98, off
	global_store_short v[102:103], v99, off offset:128
	s_waitcnt lgkmcnt(4)
	v_mfma_f32_16x16x32_bf16 v[36:39], v[78:81], v[74:77], v[36:39]
	global_store_short v[102:103], v100, off offset:256
	s_waitcnt lgkmcnt(3)
	v_mfma_f32_16x16x32_bf16 v[36:39], v[82:85], v[74:77], v[36:39]
	global_store_short v[102:103], v101, off offset:384
	s_waitcnt lgkmcnt(1)
	v_mfma_f32_16x16x32_bf16 v[36:39], v[90:93], v[86:89], v[36:39]
	s_waitcnt lgkmcnt(0)
	v_mfma_f32_16x16x32_bf16 v[36:39], v[94:97], v[86:89], v[36:39]

.LBB0_677:
	s_add_i32 s11, s27, s36
	s_add_i32 s30, s11, -6
	s_ashr_i32 s31, s30, 31
	s_lshl_b64 s[30:31], s[30:31], 13
	v_lshl_add_u64 v[102:103], v[62:63], 0, s[30:31]
	v_cvt_pk_bf16_f32 v98, v36, s0
	v_cvt_pk_bf16_f32 v99, v37, s0
	v_cvt_pk_bf16_f32 v100, v38, s0
	v_cvt_pk_bf16_f32 v101, v39, s0
	v_add_u32_e32 v0, v66, v72
	ds_read2st64_b32 v[36:37], v0 offset0:72 offset1:73
	ds_read_b32 v38, v0 offset:18944
	v_add_u32_e32 v0, v66, v73
	ds_read_b32 v39, v0 offset:18432
	ds_read_b128 v[74:77], v67
	ds_read_b128 v[78:81], v68 offset:26624
	ds_read_b128 v[82:85], v68 offset:28928
	ds_read_b128 v[86:89], v67 offset:64
	ds_read_b128 v[90:93], v68 offset:26688
	ds_read_b128 v[94:97], v68 offset:28992
	global_store_short v[102:103], v98, off
	global_store_short v[102:103], v99, off offset:128
	s_waitcnt lgkmcnt(4)
	v_mfma_f32_16x16x32_bf16 v[36:39], v[78:81], v[74:77], v[36:39]
	global_store_short v[102:103], v100, off offset:256
	s_waitcnt lgkmcnt(3)
	v_mfma_f32_16x16x32_bf16 v[36:39], v[82:85], v[74:77], v[36:39]
	global_store_short v[102:103], v101, off offset:384
	s_waitcnt lgkmcnt(1)
	v_mfma_f32_16x16x32_bf16 v[36:39], v[90:93], v[86:89], v[36:39]
	s_waitcnt lgkmcnt(0)
	v_mfma_f32_16x16x32_bf16 v[36:39], v[94:97], v[86:89], v[36:39]

.LBB0_684:
	s_add_i32 s11, s27, s36
	s_add_i32 s28, s11, -5
	s_ashr_i32 s29, s28, 31
	s_lshl_b64 s[28:29], s[28:29], 13
	v_lshl_add_u64 v[102:103], v[62:63], 0, s[28:29]
	v_cvt_pk_bf16_f32 v98, v36, s0
	v_cvt_pk_bf16_f32 v99, v37, s0
	v_cvt_pk_bf16_f32 v100, v38, s0
	v_cvt_pk_bf16_f32 v101, v39, s0
	v_add_u32_e32 v0, v69, v72
	ds_read2st64_b32 v[36:37], v0 offset0:88 offset1:89
	ds_read_b32 v38, v0 offset:23040
	v_add_u32_e32 v0, v69, v73
	ds_read_b32 v39, v0 offset:22528
	ds_read_b128 v[74:77], v67 offset:9216
	ds_read_b128 v[78:81], v68 offset:26624
	ds_read_b128 v[82:85], v68 offset:28928
	ds_read_b128 v[86:89], v67 offset:9280
	ds_read_b128 v[90:93], v68 offset:26688
	ds_read_b128 v[94:97], v68 offset:28992
	global_store_short v[102:103], v98, off
	global_store_short v[102:103], v99, off offset:128
	s_waitcnt lgkmcnt(4)
	v_mfma_f32_16x16x32_bf16 v[36:39], v[78:81], v[74:77], v[36:39]
	global_store_short v[102:103], v100, off offset:256
	s_waitcnt lgkmcnt(3)
	v_mfma_f32_16x16x32_bf16 v[36:39], v[82:85], v[74:77], v[36:39]
	global_store_short v[102:103], v101, off offset:384
	s_waitcnt lgkmcnt(1)
	v_mfma_f32_16x16x32_bf16 v[36:39], v[90:93], v[86:89], v[36:39]
	s_waitcnt lgkmcnt(0)
	v_mfma_f32_16x16x32_bf16 v[36:39], v[94:97], v[86:89], v[36:39]
